# v24 + gate/up epilogue: per-row rstd loads hoisted before the tile K-loop (dead regs), first epilogue vmcnt(0) removed
# baseline (speedup 1.0000x reference)
.LBB0_2146:
	v_lshl_add_u32 v238, s84, 8, v205
	v_ashrrev_i32_e32 v239, 31, v238
	v_lshl_add_u64 v[238:239], v[238:239], 2, s[30:31]
	global_load_dword v222, v[238:239], off
	global_load_dword v220, v[238:239], off offset:64
	global_load_dword v218, v[238:239], off offset:128
	global_load_dword v216, v[238:239], off offset:192
	global_load_dword v214, v[238:239], off offset:512
	global_load_dword v204, v[238:239], off offset:576
	global_load_dword v206, v[238:239], off offset:640
	global_load_dword v240, v[238:239], off offset:704
	s_ashr_i32 s51, s50, 31
	s_lshl_b64 s[52:53], s[50:51], 21
	s_add_u32 s52, s63, s52
	s_addc_u32 s53, s66, s53
	s_and_b64 s[54:55], s[8:9], exec
	s_cselect_b32 s51, s53, s59
	s_cselect_b32 s64, s52, s58
	s_ashr_i32 s49, s48, 31
	s_lshl_b64 s[54:55], s[48:49], 21
	s_add_u32 s54, s67, s54
	s_addc_u32 s55, s69, s55
	s_and_b64 s[60:61], s[8:9], exec
	s_cselect_b32 s49, s55, s57
	s_cselect_b32 s65, s54, s56
	s_add_u32 s95, s56, 0x100
	s_addc_u32 s97, s57, 0
	s_add_u32 s56, s58, 0x100080
	v_mov_b32_e32 v8, 0
	s_addc_u32 s57, s59, 0
	s_mov_b32 vcc_lo, -2
	v_mov_b32_e32 v9, v8
	v_mov_b32_e32 v10, v8
	v_mov_b32_e32 v11, v8
	v_mov_b32_e32 v20, v8
	v_mov_b32_e32 v21, v8
	v_mov_b32_e32 v22, v8
	v_mov_b32_e32 v23, v8
	v_mov_b32_e32 v12, v8
	v_mov_b32_e32 v13, v8
	v_mov_b32_e32 v14, v8
	v_mov_b32_e32 v15, v8
	v_mov_b32_e32 v16, v8
	v_mov_b32_e32 v17, v8
	v_mov_b32_e32 v18, v8
	v_mov_b32_e32 v19, v8
	v_mov_b32_e32 v0, v8
	v_mov_b32_e32 v1, v8
	v_mov_b32_e32 v2, v8
	v_mov_b32_e32 v3, v8
	v_mov_b32_e32 v4, v8
	v_mov_b32_e32 v5, v8
	v_mov_b32_e32 v6, v8
	v_mov_b32_e32 v7, v8
	v_mov_b32_e32 v40, v8
	v_mov_b32_e32 v41, v8
	v_mov_b32_e32 v42, v8
	v_mov_b32_e32 v43, v8
	v_mov_b32_e32 v44, v8
	v_mov_b32_e32 v45, v8
	v_mov_b32_e32 v46, v8
	v_mov_b32_e32 v47, v8
	v_mov_b32_e32 v56, v8
	v_mov_b32_e32 v57, v8
	v_mov_b32_e32 v58, v8
	v_mov_b32_e32 v59, v8
	v_mov_b32_e32 v60, v8
	v_mov_b32_e32 v61, v8
	v_mov_b32_e32 v62, v8
	v_mov_b32_e32 v63, v8
	v_mov_b32_e32 v32, v8
	v_mov_b32_e32 v33, v8
	v_mov_b32_e32 v34, v8
	v_mov_b32_e32 v35, v8
	v_mov_b32_e32 v36, v8
	v_mov_b32_e32 v37, v8
	v_mov_b32_e32 v38, v8
	v_mov_b32_e32 v39, v8
	v_mov_b32_e32 v24, v8
	v_mov_b32_e32 v25, v8
	v_mov_b32_e32 v26, v8
	v_mov_b32_e32 v27, v8
	v_mov_b32_e32 v28, v8
	v_mov_b32_e32 v29, v8
	v_mov_b32_e32 v30, v8
	v_mov_b32_e32 v31, v8
	v_mov_b32_e32 v48, v8
	v_mov_b32_e32 v49, v8
	v_mov_b32_e32 v50, v8
	v_mov_b32_e32 v51, v8
	v_mov_b32_e32 v52, v8
	v_mov_b32_e32 v53, v8
	v_mov_b32_e32 v54, v8
	v_mov_b32_e32 v55, v8
	v_mov_b32_e32 v96, v8
	v_mov_b32_e32 v97, v8
	v_mov_b32_e32 v98, v8
	v_mov_b32_e32 v99, v8
	v_mov_b32_e32 v100, v8
	v_mov_b32_e32 v101, v8
	v_mov_b32_e32 v102, v8
	v_mov_b32_e32 v103, v8
	v_mov_b32_e32 v104, v8
	v_mov_b32_e32 v105, v8
	v_mov_b32_e32 v106, v8
	v_mov_b32_e32 v107, v8
	v_mov_b32_e32 v108, v8
	v_mov_b32_e32 v109, v8
	v_mov_b32_e32 v110, v8
	v_mov_b32_e32 v111, v8
	v_mov_b32_e32 v112, v8
	v_mov_b32_e32 v113, v8
	v_mov_b32_e32 v114, v8
	v_mov_b32_e32 v115, v8
	v_mov_b32_e32 v116, v8
	v_mov_b32_e32 v117, v8
	v_mov_b32_e32 v118, v8
	v_mov_b32_e32 v119, v8
	v_mov_b32_e32 v136, v8
	v_mov_b32_e32 v137, v8
	v_mov_b32_e32 v138, v8
	v_mov_b32_e32 v139, v8
	v_mov_b32_e32 v140, v8
	v_mov_b32_e32 v141, v8
	v_mov_b32_e32 v142, v8
	v_mov_b32_e32 v143, v8
	v_mov_b32_e32 v64, v8
	v_mov_b32_e32 v65, v8
	v_mov_b32_e32 v66, v8
	v_mov_b32_e32 v67, v8
	v_mov_b32_e32 v68, v8
	v_mov_b32_e32 v69, v8
	v_mov_b32_e32 v70, v8
	v_mov_b32_e32 v71, v8
	v_mov_b32_e32 v120, v8
	v_mov_b32_e32 v121, v8
	v_mov_b32_e32 v122, v8
	v_mov_b32_e32 v123, v8
	v_mov_b32_e32 v124, v8
	v_mov_b32_e32 v125, v8
	v_mov_b32_e32 v126, v8
	v_mov_b32_e32 v127, v8
	v_mov_b32_e32 v128, v8
	v_mov_b32_e32 v129, v8
	v_mov_b32_e32 v130, v8
	v_mov_b32_e32 v131, v8
	v_mov_b32_e32 v132, v8
	v_mov_b32_e32 v133, v8
	v_mov_b32_e32 v134, v8
	v_mov_b32_e32 v135, v8
	v_mov_b32_e32 v146, v8
	v_mov_b32_e32 v147, v8
	v_mov_b32_e32 v148, v8
	v_mov_b32_e32 v149, v8
	v_mov_b32_e32 v150, v8
	v_mov_b32_e32 v151, v8
	v_mov_b32_e32 v152, v8
	v_mov_b32_e32 v153, v8
	v_add_u32_e32 v244, 0x10000, v207

.LBB0_2150:
	v_lshl_add_u32 v208, s84, 8, v205
	v_ashrrev_i32_e32 v209, 31, v208
	v_mov_b32_e32 v210, v240
	v_lshl_or_b32 v212, s85, 7, v215
	v_ashrrev_i32_e32 v213, 31, v212
	s_and_saveexec_b64 s[10:11], s[4:5]
	v_readlane_b32 s64, v251, 52
	s_xor_b64 s[56:57], exec, s[10:11]
	v_readlane_b32 s95, v251, 48
	v_readlane_b32 s97, v251, 49
	v_readlane_b32 s65, v251, 53
	s_or_saveexec_b64 s[56:57], s[56:57]
	v_pk_mul_f32 v[160:161], v[70:71], v[216:217] op_sel_hi:[1,0]
	v_pk_mul_f32 v[158:159], v[68:69], v[216:217] op_sel_hi:[1,0]
	v_pk_mul_f32 v[156:157], v[66:67], v[216:217] op_sel_hi:[1,0]
	v_pk_mul_f32 v[154:155], v[64:65], v[216:217] op_sel_hi:[1,0]
	v_pk_mul_f32 v[62:63], v[62:63], v[210:211] op_sel_hi:[1,0]
	v_pk_mul_f32 v[60:61], v[60:61], v[210:211] op_sel_hi:[1,0]
	v_pk_mul_f32 v[58:59], v[58:59], v[210:211] op_sel_hi:[1,0]
	v_pk_mul_f32 v[56:57], v[56:57], v[210:211] op_sel_hi:[1,0]
	s_xor_b64 exec, exec, s[56:57]
	s_cbranch_execz .LBB0_2155
	v_lshl_add_u32 v64, s84, 1, v219
	s_mov_b32 s10, 0xac00
	v_mad_i64_i32 v[64:65], s[10:11], v64, s10, 0
	v_lshl_add_u64 v[64:65], s[26:27], 0, v[64:65]
	v_add_u32_e32 v66, s92, v223
	s_andn2_b64 vcc, exec, s[36:37]
	v_lshl_add_u64 v[64:65], v[212:213], 2, v[64:65]
	ds_write_b128 v66, v[158:161]
	ds_write_b128 v66, v[154:157] offset:16
	s_cbranch_vccnz .LBB0_2153
	flat_store_dwordx4 v[64:65], v[158:161]
	global_store_dwordx4 v[64:65], v[154:157], off offset:16
